# F4 + down GEMM residual epilogue: the two column pieces of a row group load together (8 round trips instead of 16, counted waits)
# baseline (speedup 1.0000x reference)
.LBB1_1257:
	s_mov_b32 s26, -1
	s_movk_i32 s75, 0x2000
	v_mbcnt_lo_u32_b32 v140, s26, 0
	v_mbcnt_hi_u32_b32 v140, s26, v140
	s_lshl_b32 s26, s72, 8
	s_add_i32 s26, s26, s54
	v_and_or_b32 v142, v140, 15, s26
	s_lshl_b32 s26, s76, 8
	v_lshrrev_b32_e32 v140, 1, v140
	v_and_b32_e32 v140, 56, v140
	s_or_b32 s26, s26, s57
	v_add_u32_e32 v140, s26, v140
	s_mov_b64 s[60:61], 0xa000
	v_ashrrev_i32_e32 v141, 12, v142
	v_cmp_gt_i32_e32 vcc, s75, v142
	v_mul_hi_i32_i24_e32 v144, 0xc000, v141
	v_mul_i32_i24_e32 v141, 0xc000, v141
	v_cndmask_b32_e32 v145, 0, v144, vcc
	v_cndmask_b32_e32 v144, v227, v141, vcc
	v_ashrrev_i32_e32 v141, 31, v140
	v_ashrrev_i32_e32 v143, 31, v142
	v_lshl_add_u64 v[148:149], s[30:31], 0, v[144:145]
	v_lshlrev_b64 v[144:145], 2, v[140:141]
	v_lshl_add_u64 v[148:149], v[148:149], 0, v[144:145]
	v_lshlrev_b64 v[156:157], 12, v[142:143]
	v_lshl_add_u64 v[160:161], v[148:149], 0, s[60:61]
	v_add_co_u32_e32 v148, vcc, s90, v148
	v_lshl_add_u64 v[156:157], s[12:13], 0, v[156:157]
	v_lshlrev_b64 v[140:141], 1, v[140:141]
	v_addc_co_u32_e32 v149, vcc, 0, v149, vcc
	v_lshl_add_u64 v[162:163], v[156:157], 0, v[140:141]
	global_load_dwordx4 v[148:151], v[148:149], off
	s_nop 0
	global_load_dwordx4 v[152:155], v[160:161], off offset:16
	global_load_dwordx4 v[156:159], v[162:163], off
	global_load_dwordx4 v[166:169], v[160:161], off offset:144
	s_nop 0
	global_load_dwordx4 v[170:173], v[160:161], off offset:128
	s_nop 0
	global_load_dwordx4 v[174:177], v[162:163], off offset:64
	s_nop 0
	s_movk_i32 s26, 0x1ff0
	v_cmp_gt_i32_e32 vcc, s26, v142
	s_movk_i32 s26, 0x1fe0
	s_waitcnt vmcnt(3)
	v_lshlrev_b32_e32 v164, 16, v156
	v_and_b32_e32 v165, 0xffff0000, v156
	v_pk_fma_f32 v[126:127], v[126:127], v[148:149], v[164:165]
	v_lshlrev_b32_e32 v148, 16, v158
	v_and_b32_e32 v149, 0xffff0000, v158
	v_pk_fma_f32 v[148:149], v[122:123], v[152:153], v[148:149]
	v_lshlrev_b32_e32 v122, 16, v157
	v_and_b32_e32 v123, 0xffff0000, v157
	v_pk_fma_f32 v[128:129], v[128:129], v[150:151], v[122:123]
	v_lshlrev_b32_e32 v122, 16, v159
	v_and_b32_e32 v123, 0xffff0000, v159
	v_pk_fma_f32 v[150:151], v[124:125], v[154:155], v[122:123]
	v_cvt_pk_bf16_f32 v122, v126, v127
	v_cvt_pk_bf16_f32 v123, v128, v129
	v_cvt_pk_bf16_f32 v124, v148, v149
	v_cvt_pk_bf16_f32 v125, v150, v151
	global_store_dwordx4 v[162:163], v[122:125], off
	s_waitcnt vmcnt(1)
	v_lshlrev_b32_e32 v152, 16, v174
	v_and_b32_e32 v153, 0xffff0000, v174
	v_pk_fma_f32 v[118:119], v[118:119], v[170:171], v[152:153]
	v_lshlrev_b32_e32 v170, 16, v176
	v_and_b32_e32 v171, 0xffff0000, v176
	v_pk_fma_f32 v[166:167], v[114:115], v[166:167], v[170:171]
	v_lshlrev_b32_e32 v114, 16, v175
	v_and_b32_e32 v115, 0xffff0000, v175
	v_pk_fma_f32 v[120:121], v[120:121], v[172:173], v[114:115]
	v_lshlrev_b32_e32 v114, 16, v177
	v_and_b32_e32 v115, 0xffff0000, v177
	v_pk_fma_f32 v[168:169], v[116:117], v[168:169], v[114:115]
	v_cvt_pk_bf16_f32 v114, v118, v119
	v_cvt_pk_bf16_f32 v115, v120, v121
	v_cvt_pk_bf16_f32 v116, v166, v167
	v_cvt_pk_bf16_f32 v117, v168, v169
	v_add_u32_e32 v122, 16, v142
	global_store_dwordx4 v[162:163], v[114:117], off offset:64
	v_ashrrev_i32_e32 v123, 31, v122
	s_nop 0
	v_ashrrev_i32_e32 v114, 12, v122
	v_mul_hi_i32_i24_e32 v115, 0xc000, v114
	v_mul_i32_i24_e32 v114, 0xc000, v114
	v_cndmask_b32_e32 v115, 0, v115, vcc
	v_cndmask_b32_e32 v114, v227, v114, vcc
	v_lshl_add_u64 v[114:115], s[30:31], 0, v[114:115]
	v_lshl_add_u64 v[114:115], v[114:115], 0, v[144:145]
	v_lshlrev_b64 v[122:123], 12, v[122:123]
	v_lshl_add_u64 v[126:127], v[114:115], 0, s[60:61]
	v_add_co_u32_e32 v114, vcc, s90, v114
	v_lshl_add_u64 v[122:123], s[12:13], 0, v[122:123]
	s_nop 0
	v_addc_co_u32_e32 v115, vcc, 0, v115, vcc
	v_lshl_add_u64 v[128:129], v[122:123], 0, v[140:141]
	global_load_dwordx4 v[114:117], v[114:115], off
	s_nop 0
	global_load_dwordx4 v[118:121], v[126:127], off offset:16
	global_load_dwordx4 v[122:125], v[128:129], off
	global_load_dwordx4 v[166:169], v[126:127], off offset:144
	s_nop 0
	global_load_dwordx4 v[170:173], v[126:127], off offset:128
	s_nop 0
	global_load_dwordx4 v[174:177], v[128:129], off offset:64
	s_nop 0
	v_cmp_gt_i32_e32 vcc, s26, v142
	s_movk_i32 s26, 0x1fd0
	s_waitcnt vmcnt(3)
	v_lshlrev_b32_e32 v148, 16, v122
	v_and_b32_e32 v149, 0xffff0000, v122
	v_pk_fma_f32 v[108:109], v[108:109], v[114:115], v[148:149]
	v_lshlrev_b32_e32 v114, 16, v124
	v_and_b32_e32 v115, 0xffff0000, v124
	v_pk_fma_f32 v[114:115], v[104:105], v[118:119], v[114:115]
	v_lshlrev_b32_e32 v104, 16, v123
	v_and_b32_e32 v105, 0xffff0000, v123
	v_pk_fma_f32 v[110:111], v[110:111], v[116:117], v[104:105]
	v_lshlrev_b32_e32 v104, 16, v125
	v_and_b32_e32 v105, 0xffff0000, v125
	v_pk_fma_f32 v[116:117], v[106:107], v[120:121], v[104:105]
	v_cvt_pk_bf16_f32 v104, v108, v109
	v_cvt_pk_bf16_f32 v105, v110, v111
	v_cvt_pk_bf16_f32 v106, v114, v115
	v_cvt_pk_bf16_f32 v107, v116, v117
	global_store_dwordx4 v[128:129], v[104:107], off
	s_waitcnt vmcnt(1)
	v_lshlrev_b32_e32 v118, 16, v174
	v_and_b32_e32 v119, 0xffff0000, v174
	v_pk_fma_f32 v[100:101], v[100:101], v[170:171], v[118:119]
	v_lshlrev_b32_e32 v170, 16, v176
	v_and_b32_e32 v171, 0xffff0000, v176
	v_pk_fma_f32 v[166:167], v[96:97], v[166:167], v[170:171]
	v_lshlrev_b32_e32 v96, 16, v175
	v_and_b32_e32 v97, 0xffff0000, v175
	v_pk_fma_f32 v[102:103], v[102:103], v[172:173], v[96:97]
	v_lshlrev_b32_e32 v96, 16, v177
	v_and_b32_e32 v97, 0xffff0000, v177
	v_pk_fma_f32 v[168:169], v[98:99], v[168:169], v[96:97]
	v_cvt_pk_bf16_f32 v96, v100, v101
	v_cvt_pk_bf16_f32 v97, v102, v103
	v_cvt_pk_bf16_f32 v98, v166, v167
	v_cvt_pk_bf16_f32 v99, v168, v169
	v_add_u32_e32 v104, 32, v142
	global_store_dwordx4 v[128:129], v[96:99], off offset:64
	v_ashrrev_i32_e32 v105, 31, v104
	s_nop 0
	v_ashrrev_i32_e32 v96, 12, v104
	v_mul_hi_i32_i24_e32 v97, 0xc000, v96
	v_mul_i32_i24_e32 v96, 0xc000, v96
	v_cndmask_b32_e32 v97, 0, v97, vcc
	v_cndmask_b32_e32 v96, v227, v96, vcc
	v_lshl_add_u64 v[96:97], s[30:31], 0, v[96:97]
	v_lshl_add_u64 v[96:97], v[96:97], 0, v[144:145]
	v_lshlrev_b64 v[104:105], 12, v[104:105]
	v_lshl_add_u64 v[108:109], v[96:97], 0, s[60:61]
	v_add_co_u32_e32 v96, vcc, s90, v96
	v_lshl_add_u64 v[104:105], s[12:13], 0, v[104:105]
	s_nop 0
	v_addc_co_u32_e32 v97, vcc, 0, v97, vcc
	v_lshl_add_u64 v[110:111], v[104:105], 0, v[140:141]
	global_load_dwordx4 v[96:99], v[96:97], off
	s_nop 0
	global_load_dwordx4 v[100:103], v[108:109], off offset:16
	global_load_dwordx4 v[104:107], v[110:111], off
	global_load_dwordx4 v[166:169], v[108:109], off offset:144
	s_nop 0
	global_load_dwordx4 v[170:173], v[108:109], off offset:128
	s_nop 0
	global_load_dwordx4 v[174:177], v[110:111], off offset:64
	s_nop 0
	v_cmp_gt_i32_e32 vcc, s26, v142
	s_movk_i32 s26, 0x1f80
	s_waitcnt vmcnt(3)
	v_lshlrev_b32_e32 v114, 16, v104
	v_and_b32_e32 v115, 0xffff0000, v104
	v_pk_fma_f32 v[92:93], v[92:93], v[96:97], v[114:115]
	v_lshlrev_b32_e32 v96, 16, v106
	v_and_b32_e32 v97, 0xffff0000, v106
	v_pk_fma_f32 v[96:97], v[88:89], v[100:101], v[96:97]
	v_lshlrev_b32_e32 v88, 16, v105
	v_and_b32_e32 v89, 0xffff0000, v105
	v_pk_fma_f32 v[94:95], v[94:95], v[98:99], v[88:89]
	v_lshlrev_b32_e32 v88, 16, v107
	v_and_b32_e32 v89, 0xffff0000, v107
	v_pk_fma_f32 v[98:99], v[90:91], v[102:103], v[88:89]
	v_cvt_pk_bf16_f32 v88, v92, v93
	v_cvt_pk_bf16_f32 v89, v94, v95
	v_cvt_pk_bf16_f32 v90, v96, v97
	v_cvt_pk_bf16_f32 v91, v98, v99
	global_store_dwordx4 v[110:111], v[88:91], off
	s_waitcnt vmcnt(1)
	v_lshlrev_b32_e32 v100, 16, v174
	v_and_b32_e32 v101, 0xffff0000, v174
	v_pk_fma_f32 v[84:85], v[84:85], v[170:171], v[100:101]
	v_lshlrev_b32_e32 v170, 16, v176
	v_and_b32_e32 v171, 0xffff0000, v176
	v_pk_fma_f32 v[166:167], v[80:81], v[166:167], v[170:171]
	v_lshlrev_b32_e32 v80, 16, v175
	v_and_b32_e32 v81, 0xffff0000, v175
	v_pk_fma_f32 v[86:87], v[86:87], v[172:173], v[80:81]
	v_lshlrev_b32_e32 v80, 16, v177
	v_and_b32_e32 v81, 0xffff0000, v177
	v_pk_fma_f32 v[168:169], v[82:83], v[168:169], v[80:81]
	v_cvt_pk_bf16_f32 v80, v84, v85
	v_cvt_pk_bf16_f32 v81, v86, v87
	v_cvt_pk_bf16_f32 v82, v166, v167
	v_cvt_pk_bf16_f32 v83, v168, v169
	v_add_u32_e32 v88, 48, v142
	global_store_dwordx4 v[110:111], v[80:83], off offset:64
	v_ashrrev_i32_e32 v89, 31, v88
	s_nop 0
	v_ashrrev_i32_e32 v80, 12, v88
	v_mul_hi_i32_i24_e32 v81, 0xc000, v80
	v_mul_i32_i24_e32 v80, 0xc000, v80
	v_cndmask_b32_e32 v81, 0, v81, vcc
	v_cndmask_b32_e32 v80, v227, v80, vcc
	v_lshl_add_u64 v[80:81], s[30:31], 0, v[80:81]
	v_lshl_add_u64 v[80:81], v[80:81], 0, v[144:145]
	v_lshlrev_b64 v[88:89], 12, v[88:89]
	v_lshl_add_u64 v[92:93], v[80:81], 0, s[60:61]
	v_add_co_u32_e32 v80, vcc, s90, v80
	v_lshl_add_u64 v[88:89], s[12:13], 0, v[88:89]
	s_nop 0
	v_addc_co_u32_e32 v81, vcc, 0, v81, vcc
	v_lshl_add_u64 v[94:95], v[88:89], 0, v[140:141]
	global_load_dwordx4 v[80:83], v[80:81], off
	s_nop 0
	global_load_dwordx4 v[84:87], v[92:93], off offset:16
	global_load_dwordx4 v[88:91], v[94:95], off
	global_load_dwordx4 v[166:169], v[92:93], off offset:144
	s_nop 0
	global_load_dwordx4 v[170:173], v[92:93], off offset:128
	s_nop 0
	global_load_dwordx4 v[174:177], v[94:95], off offset:64
	s_nop 0
	v_cmp_gt_i32_e32 vcc, s26, v142
	s_movk_i32 s26, 0x1f70
	s_waitcnt vmcnt(3)
	v_lshlrev_b32_e32 v96, 16, v88
	v_and_b32_e32 v97, 0xffff0000, v88
	v_pk_fma_f32 v[76:77], v[76:77], v[80:81], v[96:97]
	v_lshlrev_b32_e32 v80, 16, v90
	v_and_b32_e32 v81, 0xffff0000, v90
	v_pk_fma_f32 v[80:81], v[72:73], v[84:85], v[80:81]
	v_lshlrev_b32_e32 v72, 16, v89
	v_and_b32_e32 v73, 0xffff0000, v89
	v_pk_fma_f32 v[78:79], v[78:79], v[82:83], v[72:73]
	v_lshlrev_b32_e32 v72, 16, v91
	v_and_b32_e32 v73, 0xffff0000, v91
	v_pk_fma_f32 v[82:83], v[74:75], v[86:87], v[72:73]
	v_cvt_pk_bf16_f32 v72, v76, v77
	v_cvt_pk_bf16_f32 v73, v78, v79
	v_cvt_pk_bf16_f32 v74, v80, v81
	v_cvt_pk_bf16_f32 v75, v82, v83
	global_store_dwordx4 v[94:95], v[72:75], off
	s_waitcnt vmcnt(1)
	v_lshlrev_b32_e32 v84, 16, v174
	v_and_b32_e32 v85, 0xffff0000, v174
	v_pk_fma_f32 v[68:69], v[68:69], v[170:171], v[84:85]
	v_lshlrev_b32_e32 v170, 16, v176
	v_and_b32_e32 v171, 0xffff0000, v176
	v_pk_fma_f32 v[166:167], v[64:65], v[166:167], v[170:171]
	v_lshlrev_b32_e32 v64, 16, v175
	v_and_b32_e32 v65, 0xffff0000, v175
	v_pk_fma_f32 v[70:71], v[70:71], v[172:173], v[64:65]
	v_lshlrev_b32_e32 v64, 16, v177
	v_and_b32_e32 v65, 0xffff0000, v177
	v_pk_fma_f32 v[168:169], v[66:67], v[168:169], v[64:65]
	v_cvt_pk_bf16_f32 v64, v68, v69
	v_cvt_pk_bf16_f32 v65, v70, v71
	v_cvt_pk_bf16_f32 v66, v166, v167
	v_cvt_pk_bf16_f32 v67, v168, v169
	v_add_u32_e32 v72, 0x80, v142
	global_store_dwordx4 v[94:95], v[64:67], off offset:64
	v_ashrrev_i32_e32 v73, 31, v72
	s_nop 0
	v_ashrrev_i32_e32 v64, 12, v72
	v_mul_hi_i32_i24_e32 v65, 0xc000, v64
	v_mul_i32_i24_e32 v64, 0xc000, v64
	v_cndmask_b32_e32 v65, 0, v65, vcc
	v_cndmask_b32_e32 v64, v227, v64, vcc
	v_lshl_add_u64 v[64:65], s[30:31], 0, v[64:65]
	v_lshl_add_u64 v[64:65], v[64:65], 0, v[144:145]
	v_lshlrev_b64 v[72:73], 12, v[72:73]
	v_lshl_add_u64 v[76:77], v[64:65], 0, s[60:61]
	v_add_co_u32_e32 v64, vcc, s90, v64
	v_lshl_add_u64 v[72:73], s[12:13], 0, v[72:73]
	s_nop 0
	v_addc_co_u32_e32 v65, vcc, 0, v65, vcc
	v_lshl_add_u64 v[78:79], v[72:73], 0, v[140:141]
	global_load_dwordx4 v[64:67], v[64:65], off
	s_nop 0
	global_load_dwordx4 v[68:71], v[76:77], off offset:16
	global_load_dwordx4 v[72:75], v[78:79], off
	global_load_dwordx4 v[166:169], v[76:77], off offset:144
	s_nop 0
	global_load_dwordx4 v[170:173], v[76:77], off offset:128
	s_nop 0
	global_load_dwordx4 v[174:177], v[78:79], off offset:64
	s_nop 0
	v_cmp_gt_i32_e32 vcc, s26, v142
	s_movk_i32 s26, 0x1f60
	s_waitcnt vmcnt(3)
	v_lshlrev_b32_e32 v80, 16, v72
	v_and_b32_e32 v81, 0xffff0000, v72
	v_pk_fma_f32 v[60:61], v[60:61], v[64:65], v[80:81]
	v_lshlrev_b32_e32 v64, 16, v74
	v_and_b32_e32 v65, 0xffff0000, v74
	v_pk_fma_f32 v[64:65], v[56:57], v[68:69], v[64:65]
	v_lshlrev_b32_e32 v56, 16, v73
	v_and_b32_e32 v57, 0xffff0000, v73
	v_pk_fma_f32 v[62:63], v[62:63], v[66:67], v[56:57]
	v_lshlrev_b32_e32 v56, 16, v75
	v_and_b32_e32 v57, 0xffff0000, v75
	v_pk_fma_f32 v[66:67], v[58:59], v[70:71], v[56:57]
	v_cvt_pk_bf16_f32 v56, v60, v61
	v_cvt_pk_bf16_f32 v57, v62, v63
	v_cvt_pk_bf16_f32 v58, v64, v65
	v_cvt_pk_bf16_f32 v59, v66, v67
	global_store_dwordx4 v[78:79], v[56:59], off
	s_waitcnt vmcnt(1)
	v_lshlrev_b32_e32 v68, 16, v174
	v_and_b32_e32 v69, 0xffff0000, v174
	v_pk_fma_f32 v[52:53], v[52:53], v[170:171], v[68:69]
	v_lshlrev_b32_e32 v170, 16, v176
	v_and_b32_e32 v171, 0xffff0000, v176
	v_pk_fma_f32 v[166:167], v[48:49], v[166:167], v[170:171]
	v_lshlrev_b32_e32 v48, 16, v175
	v_and_b32_e32 v49, 0xffff0000, v175
	v_pk_fma_f32 v[54:55], v[54:55], v[172:173], v[48:49]
	v_lshlrev_b32_e32 v48, 16, v177
	v_and_b32_e32 v49, 0xffff0000, v177
	v_pk_fma_f32 v[168:169], v[50:51], v[168:169], v[48:49]
	v_cvt_pk_bf16_f32 v48, v52, v53
	v_cvt_pk_bf16_f32 v49, v54, v55
	v_cvt_pk_bf16_f32 v50, v166, v167
	v_cvt_pk_bf16_f32 v51, v168, v169
	v_add_u32_e32 v56, 0x90, v142
	global_store_dwordx4 v[78:79], v[48:51], off offset:64
	v_ashrrev_i32_e32 v57, 31, v56
	s_nop 0
	v_ashrrev_i32_e32 v48, 12, v56
	v_mul_hi_i32_i24_e32 v49, 0xc000, v48
	v_mul_i32_i24_e32 v48, 0xc000, v48
	v_cndmask_b32_e32 v49, 0, v49, vcc
	v_cndmask_b32_e32 v48, v227, v48, vcc
	v_lshl_add_u64 v[48:49], s[30:31], 0, v[48:49]
	v_lshl_add_u64 v[48:49], v[48:49], 0, v[144:145]
	v_lshlrev_b64 v[56:57], 12, v[56:57]
	v_lshl_add_u64 v[60:61], v[48:49], 0, s[60:61]
	v_add_co_u32_e32 v48, vcc, s90, v48
	v_lshl_add_u64 v[56:57], s[12:13], 0, v[56:57]
	s_nop 0
	v_addc_co_u32_e32 v49, vcc, 0, v49, vcc
	v_lshl_add_u64 v[62:63], v[56:57], 0, v[140:141]
	global_load_dwordx4 v[48:51], v[48:49], off
	s_nop 0
	global_load_dwordx4 v[52:55], v[60:61], off offset:16
	global_load_dwordx4 v[56:59], v[62:63], off
	global_load_dwordx4 v[166:169], v[60:61], off offset:144
	s_nop 0
	global_load_dwordx4 v[170:173], v[60:61], off offset:128
	s_nop 0
	global_load_dwordx4 v[174:177], v[62:63], off offset:64
	s_nop 0
	v_cmp_gt_i32_e32 vcc, s26, v142
	s_movk_i32 s26, 0x1f50
	s_waitcnt vmcnt(3)
	v_lshlrev_b32_e32 v64, 16, v56
	v_and_b32_e32 v65, 0xffff0000, v56
	v_pk_fma_f32 v[44:45], v[44:45], v[48:49], v[64:65]
	v_lshlrev_b32_e32 v48, 16, v58
	v_and_b32_e32 v49, 0xffff0000, v58
	v_pk_fma_f32 v[48:49], v[40:41], v[52:53], v[48:49]
	v_lshlrev_b32_e32 v40, 16, v57
	v_and_b32_e32 v41, 0xffff0000, v57
	v_pk_fma_f32 v[46:47], v[46:47], v[50:51], v[40:41]
	v_lshlrev_b32_e32 v40, 16, v59
	v_and_b32_e32 v41, 0xffff0000, v59
	v_pk_fma_f32 v[50:51], v[42:43], v[54:55], v[40:41]
	v_cvt_pk_bf16_f32 v40, v44, v45
	v_cvt_pk_bf16_f32 v41, v46, v47
	v_cvt_pk_bf16_f32 v42, v48, v49
	v_cvt_pk_bf16_f32 v43, v50, v51
	global_store_dwordx4 v[62:63], v[40:43], off
	s_waitcnt vmcnt(1)
	v_lshlrev_b32_e32 v52, 16, v174
	v_and_b32_e32 v53, 0xffff0000, v174
	v_pk_fma_f32 v[36:37], v[36:37], v[170:171], v[52:53]
	v_lshlrev_b32_e32 v170, 16, v176
	v_and_b32_e32 v171, 0xffff0000, v176
	v_pk_fma_f32 v[166:167], v[32:33], v[166:167], v[170:171]
	v_lshlrev_b32_e32 v32, 16, v175
	v_and_b32_e32 v33, 0xffff0000, v175
	v_pk_fma_f32 v[38:39], v[38:39], v[172:173], v[32:33]
	v_lshlrev_b32_e32 v32, 16, v177
	v_and_b32_e32 v33, 0xffff0000, v177
	v_pk_fma_f32 v[168:169], v[34:35], v[168:169], v[32:33]
	v_cvt_pk_bf16_f32 v32, v36, v37
	v_cvt_pk_bf16_f32 v33, v38, v39
	v_cvt_pk_bf16_f32 v34, v166, v167
	v_cvt_pk_bf16_f32 v35, v168, v169
	v_add_u32_e32 v40, 0xa0, v142
	global_store_dwordx4 v[62:63], v[32:35], off offset:64
	v_ashrrev_i32_e32 v41, 31, v40
	s_nop 0
	v_ashrrev_i32_e32 v32, 12, v40
	v_mul_hi_i32_i24_e32 v33, 0xc000, v32
	v_mul_i32_i24_e32 v32, 0xc000, v32
	v_cndmask_b32_e32 v33, 0, v33, vcc
	v_cndmask_b32_e32 v32, v227, v32, vcc
	v_lshl_add_u64 v[32:33], s[30:31], 0, v[32:33]
	v_lshl_add_u64 v[32:33], v[32:33], 0, v[144:145]
	v_lshlrev_b64 v[40:41], 12, v[40:41]
	v_lshl_add_u64 v[44:45], v[32:33], 0, s[60:61]
	v_add_co_u32_e32 v32, vcc, s90, v32
	v_lshl_add_u64 v[40:41], s[12:13], 0, v[40:41]
	s_nop 0
	v_addc_co_u32_e32 v33, vcc, 0, v33, vcc
	v_lshl_add_u64 v[46:47], v[40:41], 0, v[140:141]
	global_load_dwordx4 v[32:35], v[32:33], off
	s_nop 0
	global_load_dwordx4 v[36:39], v[44:45], off offset:16
	global_load_dwordx4 v[40:43], v[46:47], off
	global_load_dwordx4 v[166:169], v[44:45], off offset:144
	s_nop 0
	global_load_dwordx4 v[170:173], v[44:45], off offset:128
	s_nop 0
	global_load_dwordx4 v[174:177], v[46:47], off offset:64
	s_nop 0
	v_cmp_gt_i32_e32 vcc, s26, v142
	s_mov_b64 s[26:27], -1
	s_waitcnt vmcnt(3)
	v_lshlrev_b32_e32 v48, 16, v40
	v_and_b32_e32 v49, 0xffff0000, v40
	v_pk_fma_f32 v[28:29], v[28:29], v[32:33], v[48:49]
	v_lshlrev_b32_e32 v32, 16, v42
	v_and_b32_e32 v33, 0xffff0000, v42
	v_pk_fma_f32 v[32:33], v[24:25], v[36:37], v[32:33]
	v_lshlrev_b32_e32 v24, 16, v41
	v_and_b32_e32 v25, 0xffff0000, v41
	v_pk_fma_f32 v[30:31], v[30:31], v[34:35], v[24:25]
	v_lshlrev_b32_e32 v24, 16, v43
	v_and_b32_e32 v25, 0xffff0000, v43
	v_pk_fma_f32 v[34:35], v[26:27], v[38:39], v[24:25]
	v_cvt_pk_bf16_f32 v24, v28, v29
	v_cvt_pk_bf16_f32 v25, v30, v31
	v_cvt_pk_bf16_f32 v26, v32, v33
	v_cvt_pk_bf16_f32 v27, v34, v35
	global_store_dwordx4 v[46:47], v[24:27], off
	s_waitcnt vmcnt(1)
	v_lshlrev_b32_e32 v36, 16, v174
	v_and_b32_e32 v37, 0xffff0000, v174
	v_pk_fma_f32 v[20:21], v[20:21], v[170:171], v[36:37]
	v_lshlrev_b32_e32 v170, 16, v176
	v_and_b32_e32 v171, 0xffff0000, v176
	v_pk_fma_f32 v[166:167], v[16:17], v[166:167], v[170:171]
	v_lshlrev_b32_e32 v16, 16, v175
	v_and_b32_e32 v17, 0xffff0000, v175
	v_pk_fma_f32 v[22:23], v[22:23], v[172:173], v[16:17]
	v_lshlrev_b32_e32 v16, 16, v177
	v_and_b32_e32 v17, 0xffff0000, v177
	v_pk_fma_f32 v[168:169], v[18:19], v[168:169], v[16:17]
	v_cvt_pk_bf16_f32 v16, v20, v21
	v_cvt_pk_bf16_f32 v17, v22, v23
	v_cvt_pk_bf16_f32 v18, v166, v167
	v_cvt_pk_bf16_f32 v19, v168, v169
	v_add_u32_e32 v24, 0xb0, v142
	global_store_dwordx4 v[46:47], v[16:19], off offset:64
	v_ashrrev_i32_e32 v25, 31, v24
	s_nop 0
	v_ashrrev_i32_e32 v16, 12, v24
	v_mul_hi_i32_i24_e32 v17, 0xc000, v16
	v_mul_i32_i24_e32 v16, 0xc000, v16
	v_cndmask_b32_e32 v17, 0, v17, vcc
	v_cndmask_b32_e32 v16, v227, v16, vcc
	v_lshl_add_u64 v[16:17], s[30:31], 0, v[16:17]
	v_lshl_add_u64 v[16:17], v[16:17], 0, v[144:145]
	v_lshlrev_b64 v[24:25], 12, v[24:25]
	v_lshl_add_u64 v[28:29], v[16:17], 0, s[60:61]
	v_add_co_u32_e32 v16, vcc, s90, v16
	v_lshl_add_u64 v[24:25], s[12:13], 0, v[24:25]
	s_nop 0
	v_addc_co_u32_e32 v17, vcc, 0, v17, vcc
	v_lshl_add_u64 v[30:31], v[24:25], 0, v[140:141]
	global_load_dwordx4 v[16:19], v[16:17], off
	s_nop 0
	global_load_dwordx4 v[20:23], v[28:29], off offset:16
	global_load_dwordx4 v[24:27], v[30:31], off
	global_load_dwordx4 v[166:169], v[28:29], off offset:144
	s_nop 0
	global_load_dwordx4 v[170:173], v[28:29], off offset:128
	s_nop 0
	global_load_dwordx4 v[174:177], v[30:31], off offset:64
	s_nop 0
	s_andn2_b64 vcc, exec, s[36:37]
	s_waitcnt vmcnt(3)
	v_lshlrev_b32_e32 v32, 16, v24
	v_and_b32_e32 v33, 0xffff0000, v24
	v_pk_fma_f32 v[12:13], v[12:13], v[16:17], v[32:33]
	v_lshlrev_b32_e32 v16, 16, v26
	v_and_b32_e32 v17, 0xffff0000, v26
	v_pk_fma_f32 v[16:17], v[8:9], v[20:21], v[16:17]
	v_lshlrev_b32_e32 v8, 16, v25
	v_and_b32_e32 v9, 0xffff0000, v25
	v_pk_fma_f32 v[14:15], v[14:15], v[18:19], v[8:9]
	v_lshlrev_b32_e32 v8, 16, v27
	v_and_b32_e32 v9, 0xffff0000, v27
	v_pk_fma_f32 v[18:19], v[10:11], v[22:23], v[8:9]
	v_cvt_pk_bf16_f32 v8, v12, v13
	v_cvt_pk_bf16_f32 v9, v14, v15
	v_cvt_pk_bf16_f32 v10, v16, v17
	v_cvt_pk_bf16_f32 v11, v18, v19
	global_store_dwordx4 v[30:31], v[8:11], off
	s_waitcnt vmcnt(1)
	v_lshlrev_b32_e32 v20, 16, v174
	v_and_b32_e32 v21, 0xffff0000, v174
	v_pk_fma_f32 v[4:5], v[4:5], v[170:171], v[20:21]
	v_lshlrev_b32_e32 v170, 16, v176
	v_and_b32_e32 v171, 0xffff0000, v176
	v_pk_fma_f32 v[166:167], v[0:1], v[166:167], v[170:171]
	v_lshlrev_b32_e32 v0, 16, v175
	v_and_b32_e32 v1, 0xffff0000, v175
	v_pk_fma_f32 v[6:7], v[6:7], v[172:173], v[0:1]
	v_lshlrev_b32_e32 v0, 16, v177
	v_and_b32_e32 v1, 0xffff0000, v177
	v_pk_fma_f32 v[168:169], v[2:3], v[168:169], v[0:1]
	v_cvt_pk_bf16_f32 v0, v4, v5
	v_cvt_pk_bf16_f32 v1, v6, v7
	v_cvt_pk_bf16_f32 v2, v166, v167
	v_cvt_pk_bf16_f32 v3, v168, v169
	global_store_dwordx4 v[30:31], v[0:3], off offset:64
	s_cbranch_vccnz .LBB1_1246
	s_andn2_b64 vcc, exec, s[18:19]
	s_cbranch_vccnz .LBB1_1245
	s_barrier
	s_branch .LBB1_1245
